# MoBA item loop: K/V rows of the step after next touched one step earlier (cache-warming loads, counted vmcnt)
# baseline (speedup 1.0000x reference)
; #define LAS __attribute__((address_space(3)))
; __device__ __forceinline__ void sub_load(Sub32& r, const bf16* kt, const bf16* vt, int lane) {
; #pragma unroll
;     for (int i = 0; i < 4; ++i) { r.k[i] = *(const u32x4*)(kt + (i * 64 + lane) * 8); r.v[i] = *(const u32x4*)(vt + (i * 64 + lane) * 8); }
; }
; __device__ __forceinline__ void sub_write(const Sub32& r, lbyte* kbuf, lbyte* vbuf, int lane) {
; #pragma unroll
;     for (int i = 0; i < 4; ++i) { const int ci = i * 64 + lane; *(LAS u32x4*)(kbuf + (ci >> 3) * KP64 + (ci & 7) * 16) = r.k[i]; *(LAS u32x4*)(vbuf + (ci >> 3) * MC_VPR + (ci & 7) * 16) = r.v[i]; }
; }
; template <bool CAUSAL> __device__ __forceinline__ void moba_span(lbyte* kbuf, lbyte* vbuf, const bf16* Kh, const bf16* Vh, int kpos0, int nsub, const s16x8* qf, int tq, bool valid, int qlo, int qhi, ...
;     Sub32 st; sub_load(st, Kh + (size_t)kpos0 * 64, Vh + (size_t)kpos0 * 64, lane);
; __device__ __forceinline__ void moba_unit2(lbyte* lds, const bf16* QKV, bf16* AO, unsigned char* part, unsigned char* part3, const float* km2, const float* rel_bias, int b, int hm, int own) {
;     ...
;         unsigned it = 0u; if (lane == 0) it = __hip_atomic_fetch_add(ctr, 1u, __ATOMIC_RELAXED, __HIP_MEMORY_SCOPE_WORKGROUP);
;         it = (unsigned)__builtin_amdgcn_readfirstlane((int)it);
;         if (it >= total) break;
;         const int n = __builtin_amdgcn_readfirstlane((int)itemn[it]);
;         const int c = (int)(it - istart[n]), idx = 32 * c + l31; const bool valid = idx < (int)cnt[n];
;         const unsigned ent = list[n * 256 + (valid ? idx : 32 * c)]; const int qid = ent & 255, slot = ent >> 8, tq = own * 256 + qid;
;         s16x8 qf[4];
; #pragma unroll
;         for (int cc = 0; cc < 4; ++cc) qf[cc] = *(const LAS s16x8*)(lds + MC_Q + qid * KP64 + (16 * cc + 8 * h) * 2);
;         f32x16 o[2];
; #pragma unroll
;         for (int r = 0; r < 16; ++r) { o[0][r] = 0.f; o[1][r] = 0.f; }
;         float m = -1e30f, l = 0.f;
.LBB0_663:
	s_or_b64 exec, exec, s[8:9]
	v_readfirstlane_b32 s11, v0
	s_mov_b64 s[8:9], -1
	s_waitcnt lgkmcnt(0)
	v_cmp_ge_u32_e32 vcc, s11, v240
	s_cbranch_vccnz .LBB0_658
	s_add_i32 s8, s11, 0
	s_add_i32 s8, s8, 0x1b000
	v_mov_b32_e32 v0, s8
	ds_read_u8 v0, v0
	v_mov_b32_e32 v6, v1
	v_mov_b32_e32 v7, v1
	v_mov_b32_e32 v8, v1
	v_mov_b32_e32 v9, v1
	s_waitcnt lgkmcnt(0)
	v_readfirstlane_b32 s8, v0
	s_lshl_b32 s9, s8, 2
	s_add_i32 s9, s9, 0
	s_add_i32 s14, s9, 0x21080
	v_mov_b32_e32 v0, s14
	ds_read_b32 v0, v0
	s_add_i32 s9, s9, 0x21000
	v_mov_b32_e32 v2, s9
	ds_read_b32 v2, v2
	s_lshl_b32 s22, s8, 8
	s_waitcnt lgkmcnt(1)
	v_sub_u32_e32 v0, s11, v0
	v_lshlrev_b32_e32 v0, 5, v0
	s_lshl_b32 s8, s8, 9
	v_or_b32_e32 v3, v0, v183
	s_add_i32 s14, s8, 0
	s_waitcnt lgkmcnt(0)
	v_cmp_lt_i32_e64 s[8:9], v3, v2
	s_ashr_i32 s23, s22, 31
	v_mov_b32_e32 v10, v1
	v_cndmask_b32_e64 v0, v0, v3, s[8:9]
	v_lshl_add_u32 v0, v0, 1, s14
	s_lshl_b64 s[14:15], s[22:23], 7
	v_add_u32_e32 v0, 0x1d000, v0
	v_lshl_add_u64 v[2:3], v[190:191], 0, s[14:15]
	ds_read_u16 v236, v0
	v_lshl_add_u64 v[4:5], v[192:193], 0, s[14:15]
	global_load_dwordx4 v[98:101], v[2:3], off
	global_load_dwordx4 v[106:109], v[2:3], off offset:1024
	global_load_dwordx4 v[122:125], v[4:5], off
	global_load_dwordx4 v[126:129], v[4:5], off offset:1024
	global_load_dwordx4 v[130:133], v[2:3], off offset:2048
	global_load_dwordx4 v[134:137], v[2:3], off offset:3072
	global_load_dwordx4 v[138:141], v[4:5], off offset:2048
	global_load_dwordx4 v[142:145], v[4:5], off offset:3072
	s_add_u32 s40, s14, 0x1000
	s_addc_u32 s41, s15, 0
	v_lshl_add_u64 v[54:55], v[190:191], 0, s[40:41]
	v_lshl_add_u64 v[56:57], v[192:193], 0, s[40:41]
	global_load_dwordx4 v[50:53], v[54:55], off
	global_load_dwordx4 v[50:53], v[54:55], off offset:1024
	global_load_dwordx4 v[50:53], v[56:57], off
	global_load_dwordx4 v[50:53], v[56:57], off offset:1024
	global_load_dwordx4 v[50:53], v[54:55], off offset:2048
	global_load_dwordx4 v[50:53], v[54:55], off offset:3072
	global_load_dwordx4 v[50:53], v[56:57], off offset:2048
	global_load_dwordx4 v[50:53], v[56:57], off offset:3072
	v_mov_b32_e32 v2, v1
	v_mov_b32_e32 v3, v1
	s_waitcnt lgkmcnt(0)
	v_and_b32_e32 v234, 0xff, v236
	v_mad_u32_u24 v0, v234, s73, v242
	ds_read_b128 v[102:105], v0
	ds_read_b128 v[110:113], v0 offset:32
	ds_read_b128 v[114:117], v0 offset:64
	ds_read_b128 v[118:121], v0 offset:96
	v_mov_b32_e32 v0, 0x3e38aa3b
	v_cndmask_b32_e64 v196, 0, v0, s[8:9]
	v_add_u32_e32 v0, s20, v234
	v_subrev_u32_e32 v235, s22, v0
	v_add_u32_e32 v0, v250, v234
	v_mov_b32_e32 v4, v1
	v_mov_b32_e32 v5, v1
	v_mov_b32_e32 v11, v1
	v_mov_b32_e32 v12, v1
	v_mov_b32_e32 v13, v1
	v_mov_b32_e32 v14, v1
	v_mov_b32_e32 v15, v1
	v_mov_b32_e32 v16, v1
	v_mov_b32_e32 v17, v1
	v_mov_b32_e32 v18, v1
	v_mov_b32_e32 v19, v1
	v_mov_b32_e32 v20, v1
	v_mov_b32_e32 v21, v1
	v_mov_b32_e32 v22, v1
	v_mov_b32_e32 v23, v1
	v_mov_b32_e32 v24, v1
	v_mov_b32_e32 v25, v1
	v_mov_b32_e32 v26, v1
	v_mov_b32_e32 v27, v1
	v_mov_b32_e32 v28, v1
	v_mov_b32_e32 v29, v1
	v_mov_b32_e32 v30, v1
	v_mov_b32_e32 v31, v1
	v_subrev_u32_e32 v237, s22, v0
	v_mov_b32_e32 v0, v1
	v_mov_b32_e32 v195, 0
	v_mov_b64_e32 v[32:33], v[30:31]
	s_mov_b32 s11, 0
	v_mov_b32_e32 v197, v196
	s_sub_i32 s14, s20, s22
	s_or_b32 s22, s22, 32
	v_mov_b32_e32 v231, 0xf149f2ca
	v_mov_b64_e32 v[30:31], v[28:29]
	v_mov_b64_e32 v[28:29], v[26:27]
	v_mov_b64_e32 v[26:27], v[24:25]
	v_mov_b64_e32 v[24:25], v[22:23]
	v_mov_b64_e32 v[22:23], v[20:21]
	v_mov_b64_e32 v[20:21], v[18:19]
	v_mov_b64_e32 v[18:19], v[16:17]
	v_mov_b64_e32 v[16:17], v[14:15]
	v_mov_b64_e32 v[14:15], v[12:13]
	v_mov_b64_e32 v[12:13], v[10:11]
	v_mov_b64_e32 v[10:11], v[8:9]
	v_mov_b64_e32 v[8:9], v[6:7]
	v_mov_b64_e32 v[6:7], v[4:5]
	v_mov_b64_e32 v[4:5], v[2:3]
	v_mov_b64_e32 v[2:3], v[0:1]
	v_mov_b32_e32 v198, 0
	v_mov_b32_e32 v199, v195
	v_mov_b32_e32 v200, 0
	v_mov_b32_e32 v201, v195
	v_mov_b32_e32 v202, 0
	v_mov_b32_e32 v203, v195
	v_mov_b32_e32 v204, 0
	v_mov_b32_e32 v205, v195
	v_mov_b32_e32 v206, 0
	v_mov_b32_e32 v207, v195
	v_mov_b32_e32 v210, 0
	v_mov_b32_e32 v211, v195
	v_mov_b32_e32 v212, 0
	v_mov_b32_e32 v213, v195
	v_mov_b32_e32 v214, 0
	v_mov_b32_e32 v215, v195
	v_mov_b32_e32 v208, 0
	v_mov_b32_e32 v209, v195
	v_mov_b32_e32 v216, 0
	v_mov_b32_e32 v217, v195
	v_mov_b32_e32 v218, 0
	v_mov_b32_e32 v219, v195
	v_mov_b32_e32 v220, 0
	v_mov_b32_e32 v221, v195
	v_mov_b32_e32 v222, 0
	v_mov_b32_e32 v223, v195
	v_mov_b32_e32 v224, 0
	v_mov_b32_e32 v225, v195
	v_mov_b32_e32 v226, 0
	v_mov_b32_e32 v227, v195
	v_mov_b32_e32 v228, 0
	v_mov_b32_e32 v229, v195
.LBB0_665:
	s_cmpk_eq_i32 s11, 0xff20
	s_cbranch_scc1 .Lmoba_lastw
	s_waitcnt vmcnt(8)
	s_branch .Lmoba_wdone

; #define LAS __attribute__((address_space(3)))
; __device__ __forceinline__ void sub_write(const Sub32& r, lbyte* kbuf, lbyte* vbuf, int lane) {
; #pragma unroll
;     for (int i = 0; i < 4; ++i) { const int ci = i * 64 + lane; *(LAS u32x4*)(kbuf + (ci >> 3) * KP64 + (ci & 7) * 16) = r.k[i]; *(LAS u32x4*)(vbuf + (ci >> 3) * MC_VPR + (ci & 7) * 16) = r.v[i]; }
; }
; template <bool CAUSAL> __device__ __forceinline__ void moba_span(lbyte* kbuf, lbyte* vbuf, const bf16* Kh, const bf16* Vh, int kpos0, int nsub, const s16x8* qf, int tq, bool valid, int qlo, int qhi, ...
;     Sub32 st; sub_load(st, Kh + (size_t)kpos0 * 64, Vh + (size_t)kpos0 * 64, lane);
; #pragma unroll 1
;     for (int su = 0; su < nsub; ++su) {
;         const int key0 = kpos0 + 32 * su;
;         sub_write(st, kbuf, vbuf, lane);
;         if (su + 1 < nsub) sub_load(st, Kh + (size_t)(key0 + 32) * 64, Vh + (size_t)(key0 + 32) * 64, lane);
.Lmoba_wdone:
	ds_write_b128 v251, v[98:101] offset:36864
	ds_write_b128 v251, v[122:125] offset:41472
	ds_write_b128 v251, v[106:109] offset:38016
	ds_write_b128 v251, v[126:129] offset:42624
	ds_write_b128 v251, v[130:133] offset:39168
	ds_write_b128 v251, v[138:141] offset:43776
	ds_write_b128 v251, v[134:137] offset:40320
	ds_write_b128 v251, v[142:145] offset:44928
	s_cbranch_scc1 .LBB0_667
	s_ashr_i32 s23, s22, 31
	s_lshl_b64 s[24:25], s[22:23], 7
	v_lshl_add_u64 v[34:35], v[190:191], 0, s[24:25]
	v_lshl_add_u64 v[36:37], v[192:193], 0, s[24:25]
	global_load_dwordx4 v[98:101], v[34:35], off
	global_load_dwordx4 v[106:109], v[34:35], off offset:1024
	global_load_dwordx4 v[122:125], v[36:37], off
	global_load_dwordx4 v[126:129], v[36:37], off offset:1024
	global_load_dwordx4 v[130:133], v[34:35], off offset:2048
	global_load_dwordx4 v[134:137], v[34:35], off offset:3072
	global_load_dwordx4 v[138:141], v[36:37], off offset:2048
	global_load_dwordx4 v[142:145], v[36:37], off offset:3072
	s_cmpk_eq_i32 s11, 0xff40
	s_cbranch_scc1 .Lmoba_nopf
	s_add_u32 s40, s24, 0x1000
	s_addc_u32 s41, s25, 0
	v_lshl_add_u64 v[54:55], v[190:191], 0, s[40:41]
	v_lshl_add_u64 v[56:57], v[192:193], 0, s[40:41]
	global_load_dwordx4 v[50:53], v[54:55], off
	global_load_dwordx4 v[50:53], v[54:55], off offset:1024
	global_load_dwordx4 v[50:53], v[56:57], off
	global_load_dwordx4 v[50:53], v[56:57], off offset:1024
	global_load_dwordx4 v[50:53], v[54:55], off offset:2048
	global_load_dwordx4 v[50:53], v[54:55], off offset:3072
	global_load_dwordx4 v[50:53], v[56:57], off offset:2048
	global_load_dwordx4 v[50:53], v[56:57], off offset:3072
; #define LDS_FENCE() asm volatile("" ::: "memory")
; template <bool CAUSAL> __device__ __forceinline__ void moba_span(lbyte* kbuf, lbyte* vbuf, const bf16* Kh, const bf16* Vh, int kpos0, int nsub, const s16x8* qf, int tq, bool valid, int qlo, int qhi, ...
;     ...
;         load_k<4>(kf, kbuf, KP64, l31, h); load_v_tr<2>(vf, vbuf, lane); LDS_FENCE();
;         qk1<4>(s[0], kf, qf);
;         const int dmin = qlo - (key0 + 31), dmax = qhi - key0;
;         const int bmin = t5_bucket(dmin > 0 ? dmin : 0), bmax = t5_bucket(dmax > 0 ? dmax : 0);
;         if (!CAUSAL && bmax - bmin <= 1) {
;             const float t0 = tab[bmin], t1 = tab[bmax]; const int th1 = thr[bmax];
;             float mxr = s[0][0];
; #pragma unroll
;             for (int r = 1; r < 16; ++r) mxr = fmaxf(mxr, s[0][r]);
;             mxr = pair_max(mxr);
;             const float cL = valid ? 0.125f * LOG2E : 0.f, bL = valid ? t0 : -INFINITY, mx = valid ? mxr * (0.125f * LOG2E) + fmaxf(t0, t1) : -INFINITY;
;             const bool grow = mx > m + 8.0f; const float mn = grow ? mx : m, off = bL - mn, offB = off + (t1 - t0);
;             if (__any(grow)) { const float alpha = __builtin_amdgcn_exp2f(m - mn); l *= alpha; o[0] = o[0] * alpha; o[1] = o[1] * alpha; }
;             m = mn;
;             const int x1 = (bmax > bmin) ? tq - key0 - th1 : -0x40000000; f32x2_t sum2 = {0.f, 0.f};
; #pragma unroll
;             for (int r = 0; r < 16; r += 2) { const int kk = kkrow(r, h);
;                 const f32x2_t ob = {x1 >= kk ? offB : off, x1 >= kk + 1 ? offB : off}; f32x2_t v = {s[0][r], s[0][r + 1]}; v = v * (f32x2_t){cL, cL} + ob;
;                 const float e0 = __builtin_amdgcn_exp2f(v.x), e1 = __builtin_amdgcn_exp2f(v.y); s[0][r] = e0; s[0][r + 1] = e1; sum2 += (f32x2_t){e0, e1}; }
;             l += pair_sum(sum2.x + sum2.y);
;         } else {
;             float bb[16];
; #pragma unroll
;             for (int r = 0; r < 16; ++r) { int dist = tq - (key0 + kkrow(r, h)); dist = dist > 0 ? dist : 0; bb[r] = dtab[dist < MC_NDT - 1 ? dist : MC_NDT - 1]; }
;             LDS_FENCE();
; #pragma unroll
;             for (int r = 0; r < 16; ++r) { const int dist = tq - (key0 + kkrow(r, h)); const bool ok = valid && (!CAUSAL || dist >= 0); s[0][r] = ok ? s[0][r] * (0.125f * LOG2E) + bb[r] : -INFINITY; }
;             softmax_upd<1, 2>(s, m, l, o);
.Lmoba_nopf:
.LBB0_667:
	ds_read_b128 v[34:37], v252 offset:36864
	ds_read_b128 v[38:41], v252 offset:36896
	ds_read_b128 v[42:45], v252 offset:36928
	ds_read_b128 v[46:49], v252 offset:36960
	ds_read_b64_tr_b16 v[158:159], v253 offset:41472
	ds_read_b64_tr_b16 v[160:161], v253 offset:42048
	ds_read_b64_tr_b16 v[156:157], v253 offset:42112
	ds_read_b64_tr_b16 v[154:155], v253 offset:41536
	s_waitcnt lgkmcnt(7)
	v_mfma_f32_32x32x16_bf16 v[66:81], v[34:37], v[102:105], 0
	s_add_i32 s15, s14, s11
	s_sub_i32 s17, s15, 31
	s_max_i32 s23, s17, 16
	s_flbit_i32_b32 s24, s23
	s_lshl_b32 s24, s24, 1
	s_sub_i32 s26, 62, s24
	s_add_i32 s21, s15, 0xff
	s_max_i32 s15, s17, 0
	s_mul_i32 s23, s23, s23
	s_lshl_b32 s24, 2, s26
	s_waitcnt lgkmcnt(6)
	v_mfma_f32_32x32x16_bf16 v[66:81], v[38:41], v[110:113], v[66:81]
	s_cmp_ge_u32 s23, s24
	s_cselect_b32 s23, 1, 0
	ds_read_b64_tr_b16 v[150:151], v253 offset:43776
	ds_read_b64_tr_b16 v[152:153], v253 offset:44352
	ds_read_b64_tr_b16 v[148:149], v253 offset:44416
	ds_read_b64_tr_b16 v[146:147], v253 offset:43840
	s_or_b32 s23, s26, s23
	s_min_u32 s23, s23, 23
	s_add_i32 s23, s23, 8
	s_cmp_lt_i32 s17, 16
	s_waitcnt lgkmcnt(9)
	v_mfma_f32_32x32x16_bf16 v[66:81], v[42:45], v[114:117], v[66:81]
	s_cselect_b32 s15, s15, s23
	s_max_i32 s23, s21, 16
	s_flbit_i32_b32 s24, s23
	s_lshl_b32 s24, s24, 1
	s_sub_i32 s26, 62, s24
	s_max_i32 s17, s21, 0
	s_mul_i32 s23, s23, s23
	s_lshl_b32 s24, 2, s26
	s_cmp_ge_u32 s23, s24
	s_cselect_b32 s23, 1, 0
	s_waitcnt lgkmcnt(8)
	v_mfma_f32_32x32x16_bf16 v[66:81], v[46:49], v[118:121], v[66:81]
	s_or_b32 s23, s26, s23
	s_min_u32 s23, s23, 23
	s_add_i32 s23, s23, 8
	s_cmp_lt_i32 s21, 16
	s_cselect_b32 s17, s17, s23
	s_sub_i32 s21, s17, s15
	s_mov_b64 s[24:25], -1
	s_cmp_gt_i32 s21, 1
	v_add_f32_e32 v0, 0x41000000, v231
	s_cbranch_scc0 .LBB0_671
	v_add_u32_e32 v34, s11, v237
	v_med3_i32 v35, v34, 0, v239
	v_add_u32_e32 v36, -1, v34
	v_add_u32_e32 v37, -2, v34
	v_add_u32_e32 v38, -3, v34
	v_add_u32_e32 v39, -8, v34
	v_add_u32_e32 v40, -9, v34
	v_add_u32_e32 v41, -10, v34
	v_add_u32_e32 v42, -11, v34
	v_add_u32_e32 v43, -16, v34
	v_subrev_u32_e32 v44, 17, v34
	v_subrev_u32_e32 v45, 18, v34
	v_subrev_u32_e32 v46, 19, v34
	v_subrev_u32_e32 v47, 24, v34
	v_subrev_u32_e32 v48, 25, v34
	v_subrev_u32_e32 v49, 26, v34
	v_subrev_u32_e32 v34, 27, v34
	v_med3_i32 v36, v36, 0, v239
	v_med3_i32 v37, v37, 0, v239
	v_med3_i32 v38, v38, 0, v239
	v_med3_i32 v39, v39, 0, v239
	v_med3_i32 v40, v40, 0, v239
	v_med3_i32 v41, v41, 0, v239
	v_med3_i32 v42, v42, 0, v239
	v_med3_i32 v43, v43, 0, v239
	v_med3_i32 v44, v44, 0, v239
	v_med3_i32 v45, v45, 0, v239
	v_med3_i32 v46, v46, 0, v239
	v_med3_i32 v47, v47, 0, v239
	v_med3_i32 v48, v48, 0, v239
	v_med3_i32 v49, v49, 0, v239
	v_med3_i32 v34, v34, 0, v239
	v_lshl_add_u32 v35, v35, 2, s82
	v_lshl_add_u32 v36, v36, 2, s82
	v_lshl_add_u32 v37, v37, 2, s82
	v_lshl_add_u32 v38, v38, 2, s82
	v_lshl_add_u32 v39, v39, 2, s82
	v_lshl_add_u32 v40, v40, 2, s82
	v_lshl_add_u32 v41, v41, 2, s82
	v_lshl_add_u32 v42, v42, 2, s82
	v_lshl_add_u32 v43, v43, 2, s82
	v_lshl_add_u32 v44, v44, 2, s82
	v_lshl_add_u32 v45, v45, 2, s82
	v_lshl_add_u32 v46, v46, 2, s82
	v_lshl_add_u32 v47, v47, 2, s82
	v_lshl_add_u32 v48, v48, 2, s82
	v_lshl_add_u32 v49, v49, 2, s82
	v_lshl_add_u32 v34, v34, 2, s82
	ds_read_b32 v35, v35
	ds_read_b32 v36, v36
	ds_read_b32 v37, v37
	ds_read_b32 v38, v38
	ds_read_b32 v39, v39
	ds_read_b32 v40, v40
	ds_read_b32 v41, v41
	ds_read_b32 v42, v42
	ds_read_b32 v43, v43
	ds_read_b32 v44, v44
	ds_read_b32 v45, v45
	ds_read_b32 v46, v46
	ds_read_b32 v47, v47
	ds_read_b32 v48, v48
	ds_read_b32 v49, v49
	ds_read_b32 v34, v34
	s_waitcnt lgkmcnt(14)
	v_fmac_f32_e32 v35, 0x3e38aa3b, v66
	v_fmac_f32_e32 v36, 0x3e38aa3b, v67
	v_cndmask_b32_e64 v82, v238, v35, s[8:9]
	v_cndmask_b32_e64 v83, v238, v36, s[8:9]
	s_waitcnt lgkmcnt(13)
	v_fmac_f32_e32 v37, 0x3e38aa3b, v68
	s_waitcnt lgkmcnt(12)
	v_fmac_f32_e32 v38, 0x3e38aa3b, v69
	s_waitcnt lgkmcnt(0)
	v_fmac_f32_e32 v34, 0x3e38aa3b, v81
	v_cndmask_b32_e64 v84, v238, v37, s[8:9]
	v_cndmask_b32_e64 v85, v238, v38, s[8:9]
	v_fmac_f32_e32 v39, 0x3e38aa3b, v70
	v_fmac_f32_e32 v40, 0x3e38aa3b, v71
	v_cndmask_b32_e64 v97, v238, v34, s[8:9]
	v_max_f32_e32 v34, v82, v83
	v_cndmask_b32_e64 v86, v238, v39, s[8:9]
	v_cndmask_b32_e64 v87, v238, v40, s[8:9]
	v_fmac_f32_e32 v41, 0x3e38aa3b, v72
	v_fmac_f32_e32 v42, 0x3e38aa3b, v73
	v_max3_f32 v34, v34, v84, v85
	v_cndmask_b32_e64 v88, v238, v41, s[8:9]
	v_cndmask_b32_e64 v89, v238, v42, s[8:9]
	v_fmac_f32_e32 v43, 0x3e38aa3b, v74
	v_fmac_f32_e32 v44, 0x3e38aa3b, v75
	v_max3_f32 v34, v34, v86, v87
	v_cndmask_b32_e64 v90, v238, v43, s[8:9]
	v_cndmask_b32_e64 v91, v238, v44, s[8:9]
	v_fmac_f32_e32 v45, 0x3e38aa3b, v76
	v_fmac_f32_e32 v46, 0x3e38aa3b, v77
	v_max3_f32 v34, v34, v88, v89
	v_cndmask_b32_e64 v92, v238, v45, s[8:9]
	v_cndmask_b32_e64 v93, v238, v46, s[8:9]
	v_fmac_f32_e32 v47, 0x3e38aa3b, v78
	v_fmac_f32_e32 v48, 0x3e38aa3b, v79
	v_max3_f32 v34, v34, v90, v91
	v_cndmask_b32_e64 v94, v238, v47, s[8:9]
	v_cndmask_b32_e64 v95, v238, v48, s[8:9]
	v_fmac_f32_e32 v49, 0x3e38aa3b, v80
	v_max3_f32 v34, v34, v92, v93
	v_cndmask_b32_e64 v96, v238, v49, s[8:9]
	v_max3_f32 v34, v34, v94, v95
	v_max3_f32 v34, v34, v96, v97
	v_mov_b32_e32 v35, v34
	s_nop 1
	v_permlane32_swap_b32_e32 v34, v35
	v_max_f32_e32 v35, v35, v35
	v_max_f32_e32 v34, v34, v34
	v_max_f32_e32 v34, v34, v35
	v_cmp_gt_f32_e32 vcc, v34, v0
	v_mov_b32_e32 v162, v195
	s_nop 0
	v_cndmask_b32_e32 v194, v231, v34, vcc
	s_cbranch_vccz .LBB0_670
	v_sub_f32_e32 v34, v231, v194
	v_exp_f32_e32 v34, v34
	s_nop 0
	v_mul_f32_e32 v162, v195, v34
	v_pk_mul_f32 v[32:33], v[32:33], v[34:35] op_sel_hi:[1,0]
	v_pk_mul_f32 v[30:31], v[30:31], v[34:35] op_sel_hi:[1,0]
	v_pk_mul_f32 v[28:29], v[28:29], v[34:35] op_sel_hi:[1,0]
	v_pk_mul_f32 v[26:27], v[26:27], v[34:35] op_sel_hi:[1,0]
	v_pk_mul_f32 v[24:25], v[24:25], v[34:35] op_sel_hi:[1,0]
	v_pk_mul_f32 v[22:23], v[22:23], v[34:35] op_sel_hi:[1,0]
	v_pk_mul_f32 v[20:21], v[20:21], v[34:35] op_sel_hi:[1,0]
	v_pk_mul_f32 v[16:17], v[16:17], v[34:35] op_sel_hi:[1,0]
	v_pk_mul_f32 v[14:15], v[14:15], v[34:35] op_sel_hi:[1,0]
	v_pk_mul_f32 v[12:13], v[12:13], v[34:35] op_sel_hi:[1,0]
	v_pk_mul_f32 v[10:11], v[10:11], v[34:35] op_sel_hi:[1,0]
	v_pk_mul_f32 v[8:9], v[8:9], v[34:35] op_sel_hi:[1,0]
	v_pk_mul_f32 v[6:7], v[6:7], v[34:35] op_sel_hi:[1,0]
	v_pk_mul_f32 v[4:5], v[4:5], v[34:35] op_sel_hi:[1,0]
	v_pk_mul_f32 v[18:19], v[18:19], v[34:35] op_sel_hi:[1,0]
	v_pk_mul_f32 v[2:3], v[2:3], v[34:35] op_sel_hi:[1,0]
